# GEMM K-loop: drop 9 compiler-duplicated s_waitcnt lgkmcnt(0) directly behind identical asm waits
# speedup vs baseline: 1.0243x; 1.0035x over previous
; #define PG8_STAGE(bufoff, gbase, voff) do { _Pragma("unroll") for (int _i = 0; _i < 2; ++_i) \
;         __builtin_amdgcn_global_load_lds((const unsigned*)((const char*)(gbase) + (voff)[_i]), (LAS unsigned*)(lds + (bufoff) + ldsw + _i * 8192), 16, 0, 0); } while (0)
; #define PG8_LDA(dst, b, h) do { _Pragma("unroll") for (int m = 0; m < 4; ++m) _Pragma("unroll") for (int k = 0; k < 2; ++k) dst[m][k] = *(const LAS bf16x8*)(lds + PG8_SA(b, h) + aoff + m * 2048 + k * 1024); } while (0)
; #define PG8_LDB(dst, b, h) do { _Pragma("unroll") for (int n = 0; n < 2; ++n) _Pragma("unroll") for (int k = 0; k < 2; ++k) dst[n][k] = *(const LAS bf16x8*)(lds + PG8_SB(b, h) + boff + n * 2048 + k * 1024); } while (0)
; #define PG8_MMA(ai, bj, At, Bt) do { __builtin_amdgcn_s_setprio(1); _Pragma("unroll") for (int m = 0; m < 4; ++m) _Pragma("unroll") for (int n = 0; n < 2; ++n) _Pragma("unroll") for (int k = 0; k < 2; ++k) \
;         acc[ai][bj][m][n] = __builtin_amdgcn_mfma_f32_16x16x32_bf16(Bt[n][k], At[m][k], acc[ai][bj][m][n], 0, 0, 0); __builtin_amdgcn_s_setprio(0); } while (0)
; #define PG8_WAIT_V(n) asm volatile("s_waitcnt vmcnt(" #n ")" ::: "memory")
; #define PG8_WAIT_L(n) asm volatile("s_waitcnt lgkmcnt(" #n ")" ::: "memory")
; #define PG8_BAR __builtin_amdgcn_s_barrier()
; #define PG8_SCHED __builtin_amdgcn_sched_barrier(0)
; __device__ __forceinline__ void gemm_phase(const int bid, const int nblk, LAS unsigned char* lds, const int garg, const int chunk, const Params& p) {
;     ...
;             PG8_LDB(B0, 0, 0); PG8_SCHED; PG8_LDA(At, 0, 0); PG8_STAGE(PG8_SA(1, 1), a1 + hstepA, voffA);
;             PG8_WAIT_L(8); PG8_BAR; PG8_WAIT_L(0); PG8_MMA(0, 0, At, B0); PG8_BAR; PG8_SCHED;
;             PG8_LDB(B1, 0, 1); PG8_STAGE(PG8_SB(0, 0), b2, voffB);
;             PG8_BAR; PG8_WAIT_L(0); PG8_MMA(0, 1, At, B1); PG8_BAR;
;             PG8_LDA(At, 0, 1); PG8_STAGE(PG8_SA(0, 0), a2, voffA);
;             PG8_BAR; PG8_WAIT_L(0); PG8_MMA(1, 0, At, B0); PG8_BAR; PG8_SCHED;
;             PG8_STAGE(PG8_SB(0, 1), b2 + hstepB, voffB);
;             PG8_WAIT_V(6); PG8_BAR; PG8_MMA(1, 1, At, B1); PG8_BAR;
.LBB0_439:
	v_readlane_b32 s10, v254, 62
	v_readlane_b32 s11, v254, 63
	s_andn2_b64 vcc, exec, s[10:11]
	s_cbranch_vccnz .LBB0_442
	s_add_u32 s2, s2, 0x80
	s_addc_u32 s3, s3, 0
	s_add_u32 s14, s8, 0x100
	s_addc_u32 s15, s9, 0
	s_mov_b32 s8, 0
	s_waitcnt vmcnt(0)
	s_add_i32 s30, s8, 2
	s_add_u32 s12, s2, 0x80
	s_addc_u32 s9, s3, 0
	s_add_i32 s31, 0, 0x10000
	v_add_u32_e32 v10, s31, v234
	ds_read_b128 v[134:137], v10
	ds_read_b128 v[138:141], v10 offset:1024
	ds_read_b128 v[142:145], v10 offset:2048
	ds_read_b128 v[146:149], v10 offset:3072
	s_cmp_eq_u32 s27, s8
	s_cselect_b32 s8, s74, s12
	s_cselect_b32 s9, s75, s9
	s_cselect_b32 s13, s79, s15
	s_cselect_b32 s12, s78, s14
	v_lshl_add_u64 v[12:13], s[2:3], 0, v[176:177]
	s_add_i32 m0, s65, 0xc000
	ds_read_b128 v[150:153], v240
	ds_read_b128 v[154:157], v240 offset:1024
	ds_read_b128 v[182:185], v240 offset:2048
	ds_read_b128 v[186:189], v240 offset:3072
	ds_read_b128 v[190:193], v240 offset:4096
	ds_read_b128 v[194:197], v240 offset:5120
	ds_read_b128 v[198:201], v240 offset:6144
	ds_read_b128 v[202:205], v240 offset:7168
	global_load_lds_dwordx4 v[12:13], off
	v_lshl_add_u64 v[12:13], s[2:3], 0, v[178:179]
	s_add_i32 m0, s65, 0xe000
	s_nop 0
	global_load_lds_dwordx4 v[12:13], off
	s_waitcnt lgkmcnt(8)
	s_barrier
	s_waitcnt lgkmcnt(0)
	s_setprio 1
	v_mfma_f32_16x16x32_bf16 v[130:133], v[134:137], v[150:153], 0
	v_mfma_f32_16x16x32_bf16 v[126:129], v[142:145], v[150:153], 0
	v_mfma_f32_16x16x32_bf16 v[114:117], v[134:137], v[182:185], 0
	v_mfma_f32_16x16x32_bf16 v[110:113], v[142:145], v[182:185], 0
	v_mfma_f32_16x16x32_bf16 v[98:101], v[134:137], v[190:193], 0
	v_mfma_f32_16x16x32_bf16 v[94:97], v[142:145], v[190:193], 0
	v_mfma_f32_16x16x32_bf16 v[82:85], v[134:137], v[198:201], 0
	v_mfma_f32_16x16x32_bf16 v[78:81], v[142:145], v[198:201], 0
	v_mfma_f32_16x16x32_bf16 v[130:133], v[138:141], v[154:157], v[130:133]
	v_mfma_f32_16x16x32_bf16 v[126:129], v[146:149], v[154:157], v[126:129]
	v_mfma_f32_16x16x32_bf16 v[114:117], v[138:141], v[186:189], v[114:117]
	v_mfma_f32_16x16x32_bf16 v[110:113], v[146:149], v[186:189], v[110:113]
	v_mfma_f32_16x16x32_bf16 v[98:101], v[138:141], v[194:197], v[98:101]
	v_mfma_f32_16x16x32_bf16 v[94:97], v[146:149], v[194:197], v[94:97]
	v_mfma_f32_16x16x32_bf16 v[82:85], v[138:141], v[202:205], v[82:85]
	v_mfma_f32_16x16x32_bf16 v[78:81], v[146:149], v[202:205], v[78:81]
	s_setprio 0
	s_barrier
	s_add_i32 s36, 0, 0x14000
	s_add_i32 s31, s31, s64
	v_add_u32_e32 v10, s36, v234
	v_lshl_add_u64 v[210:211], s[12:13], 0, v[164:165]
	s_mov_b32 m0, s31
	ds_read_b128 v[206:209], v10
	ds_read_b128 v[242:245], v10 offset:1024
	ds_read_b128 v[246:249], v10 offset:2048
	ds_read_b128 v[250:253], v10 offset:3072
	global_load_lds_dwordx4 v[210:211], off
	v_lshl_add_u64 v[216:217], s[12:13], 0, v[160:161]
	s_add_i32 m0, s31, 0x2000
	s_nop 0
	global_load_lds_dwordx4 v[216:217], off
	s_barrier
	s_waitcnt lgkmcnt(0)
	s_setprio 1
	v_mfma_f32_16x16x32_bf16 v[122:125], v[206:209], v[150:153], 0
	v_mfma_f32_16x16x32_bf16 v[118:121], v[246:249], v[150:153], 0
	v_mfma_f32_16x16x32_bf16 v[106:109], v[206:209], v[182:185], 0
	v_mfma_f32_16x16x32_bf16 v[102:105], v[246:249], v[182:185], 0
	v_mfma_f32_16x16x32_bf16 v[90:93], v[206:209], v[190:193], 0
	v_mfma_f32_16x16x32_bf16 v[86:89], v[246:249], v[190:193], 0
	v_mfma_f32_16x16x32_bf16 v[74:77], v[206:209], v[198:201], 0
	v_mfma_f32_16x16x32_bf16 v[70:73], v[246:249], v[198:201], 0
	v_mfma_f32_16x16x32_bf16 v[122:125], v[242:245], v[154:157], v[122:125]
	v_mfma_f32_16x16x32_bf16 v[118:121], v[250:253], v[154:157], v[118:121]
	v_mfma_f32_16x16x32_bf16 v[106:109], v[242:245], v[186:189], v[106:109]
	v_mfma_f32_16x16x32_bf16 v[102:105], v[250:253], v[186:189], v[102:105]
	v_mfma_f32_16x16x32_bf16 v[90:93], v[242:245], v[194:197], v[90:93]
	v_mfma_f32_16x16x32_bf16 v[86:89], v[250:253], v[194:197], v[86:89]
	v_mfma_f32_16x16x32_bf16 v[74:77], v[242:245], v[202:205], v[74:77]
	v_mfma_f32_16x16x32_bf16 v[70:73], v[250:253], v[202:205], v[70:73]
	s_setprio 0
	s_mov_b32 m0, s65
	v_lshl_add_u64 v[222:223], s[8:9], 0, v[162:163]
	s_barrier
	ds_read_b128 v[150:153], v240 offset:16384
	ds_read_b128 v[154:157], v240 offset:17408
	ds_read_b128 v[182:185], v240 offset:18432
	ds_read_b128 v[186:189], v240 offset:19456
	ds_read_b128 v[190:193], v240 offset:20480
	ds_read_b128 v[194:197], v240 offset:21504
	ds_read_b128 v[198:201], v240 offset:22528
	ds_read_b128 v[202:205], v240 offset:23552
	global_load_lds_dwordx4 v[222:223], off
	v_lshl_add_u64 v[224:225], s[8:9], 0, v[8:9]
	s_mov_b32 m0, s71
	s_nop 0
	global_load_lds_dwordx4 v[224:225], off
	s_barrier
	s_waitcnt lgkmcnt(0)
	s_setprio 1
	v_mfma_f32_16x16x32_bf16 v[66:69], v[134:137], v[150:153], 0
	v_mfma_f32_16x16x32_bf16 v[62:65], v[142:145], v[150:153], 0
	v_mfma_f32_16x16x32_bf16 v[50:53], v[134:137], v[182:185], 0
	v_mfma_f32_16x16x32_bf16 v[46:49], v[142:145], v[182:185], 0
	v_mfma_f32_16x16x32_bf16 v[34:37], v[134:137], v[190:193], 0
	v_mfma_f32_16x16x32_bf16 v[30:33], v[142:145], v[190:193], 0
	v_mfma_f32_16x16x32_bf16 v[18:21], v[134:137], v[198:201], 0
	v_mfma_f32_16x16x32_bf16 v[12:15], v[142:145], v[198:201], 0
	v_mfma_f32_16x16x32_bf16 v[66:69], v[138:141], v[154:157], v[66:69]
	v_mfma_f32_16x16x32_bf16 v[62:65], v[146:149], v[154:157], v[62:65]
	v_mfma_f32_16x16x32_bf16 v[50:53], v[138:141], v[186:189], v[50:53]
	v_mfma_f32_16x16x32_bf16 v[46:49], v[146:149], v[186:189], v[46:49]
	v_mfma_f32_16x16x32_bf16 v[34:37], v[138:141], v[194:197], v[34:37]
	v_mfma_f32_16x16x32_bf16 v[30:33], v[146:149], v[194:197], v[30:33]
	v_mfma_f32_16x16x32_bf16 v[18:21], v[138:141], v[202:205], v[18:21]
	v_mfma_f32_16x16x32_bf16 v[12:15], v[146:149], v[202:205], v[12:15]
	s_setprio 0
	s_barrier
; #define PG8_STAGE(bufoff, gbase, voff) do { _Pragma("unroll") for (int _i = 0; _i < 2; ++_i) \
;         __builtin_amdgcn_global_load_lds((const unsigned*)((const char*)(gbase) + (voff)[_i]), (LAS unsigned*)(lds + (bufoff) + ldsw + _i * 8192), 16, 0, 0); } while (0)
; #define PG8_LDA(dst, b, h) do { _Pragma("unroll") for (int m = 0; m < 4; ++m) _Pragma("unroll") for (int k = 0; k < 2; ++k) dst[m][k] = *(const LAS bf16x8*)(lds + PG8_SA(b, h) + aoff + m * 2048 + k * 1024); } while (0)
; #define PG8_LDB(dst, b, h) do { _Pragma("unroll") for (int n = 0; n < 2; ++n) _Pragma("unroll") for (int k = 0; k < 2; ++k) dst[n][k] = *(const LAS bf16x8*)(lds + PG8_SB(b, h) + boff + n * 2048 + k * 1024); } while (0)
; #define PG8_MMA(ai, bj, At, Bt) do { __builtin_amdgcn_s_setprio(1); _Pragma("unroll") for (int m = 0; m < 4; ++m) _Pragma("unroll") for (int n = 0; n < 2; ++n) _Pragma("unroll") for (int k = 0; k < 2; ++k) \
;         acc[ai][bj][m][n] = __builtin_amdgcn_mfma_f32_16x16x32_bf16(Bt[n][k], At[m][k], acc[ai][bj][m][n], 0, 0, 0); __builtin_amdgcn_s_setprio(0); } while (0)
; #define PG8_WAIT_V(n) asm volatile("s_waitcnt vmcnt(" #n ")" ::: "memory")
; #define PG8_WAIT_L(n) asm volatile("s_waitcnt lgkmcnt(" #n ")" ::: "memory")
; #define PG8_BAR __builtin_amdgcn_s_barrier()
; #define PG8_SCHED __builtin_amdgcn_sched_barrier(0)
; __device__ __forceinline__ void gemm_phase(const int bid, const int nblk, LAS unsigned char* lds, const int garg, const int chunk, const Params& p) {
;     ...
;             PG8_LDB(B0, 0, 0); PG8_SCHED; PG8_LDA(At, 0, 0); PG8_STAGE(PG8_SA(1, 1), a1 + hstepA, voffA);
;             PG8_WAIT_L(8); PG8_BAR; PG8_WAIT_L(0); PG8_MMA(0, 0, At, B0); PG8_BAR; PG8_SCHED;
;             PG8_LDB(B1, 0, 1); PG8_STAGE(PG8_SB(0, 0), b2, voffB);
;             PG8_BAR; PG8_WAIT_L(0); PG8_MMA(0, 1, At, B1); PG8_BAR;
;             PG8_LDA(At, 0, 1); PG8_STAGE(PG8_SA(0, 0), a2, voffA);
;             PG8_BAR; PG8_WAIT_L(0); PG8_MMA(1, 0, At, B0); PG8_BAR; PG8_SCHED;
;             PG8_STAGE(PG8_SB(0, 1), b2 + hstepB, voffB);
;             PG8_WAIT_V(6); PG8_BAR; PG8_MMA(1, 1, At, B1); PG8_BAR;
	s_add_u32 s12, s12, s66
	s_addc_u32 s13, s13, s67
	s_add_i32 s31, s36, s64
	v_lshl_add_u64 v[220:221], s[12:13], 0, v[164:165]
	s_mov_b32 m0, s31
	v_lshl_add_u64 v[226:227], s[12:13], 0, v[160:161]
	global_load_lds_dwordx4 v[220:221], off
	s_add_i32 m0, s31, 0x2000
	s_nop 0
	global_load_lds_dwordx4 v[226:227], off
	s_waitcnt vmcnt(6)
	s_barrier
	s_setprio 1
	v_mfma_f32_16x16x32_bf16 v[58:61], v[206:209], v[150:153], 0
	v_mfma_f32_16x16x32_bf16 v[54:57], v[246:249], v[150:153], 0
	v_mfma_f32_16x16x32_bf16 v[42:45], v[206:209], v[182:185], 0
	v_mfma_f32_16x16x32_bf16 v[38:41], v[246:249], v[182:185], 0
	v_mfma_f32_16x16x32_bf16 v[26:29], v[206:209], v[190:193], 0
	v_mfma_f32_16x16x32_bf16 v[22:25], v[246:249], v[190:193], 0
	v_mfma_f32_16x16x32_bf16 v[4:7], v[206:209], v[198:201], 0
	v_mfma_f32_16x16x32_bf16 v[0:3], v[246:249], v[198:201], 0
	v_mfma_f32_16x16x32_bf16 v[58:61], v[242:245], v[154:157], v[58:61]
	v_mfma_f32_16x16x32_bf16 v[54:57], v[250:253], v[154:157], v[54:57]
	v_mfma_f32_16x16x32_bf16 v[42:45], v[242:245], v[186:189], v[42:45]
	v_mfma_f32_16x16x32_bf16 v[38:41], v[250:253], v[186:189], v[38:41]
	v_mfma_f32_16x16x32_bf16 v[26:29], v[242:245], v[194:197], v[26:29]
	v_mfma_f32_16x16x32_bf16 v[22:25], v[250:253], v[194:197], v[22:25]
	v_mfma_f32_16x16x32_bf16 v[4:7], v[242:245], v[202:205], v[4:7]
	v_mfma_f32_16x16x32_bf16 v[0:3], v[250:253], v[202:205], v[0:3]
	s_setprio 0
	s_branch .Lk_mid
.LBB0_441:
	s_add_i32 s30, s8, 2
	s_add_u32 s12, s2, 0x80
	s_addc_u32 s9, s3, 0
	s_add_i32 s31, 0, 0x10000
	v_add_u32_e32 v10, s31, v234
	ds_read_b128 v[134:137], v10
	ds_read_b128 v[138:141], v10 offset:1024
	ds_read_b128 v[142:145], v10 offset:2048
	ds_read_b128 v[146:149], v10 offset:3072
	s_cmp_eq_u32 s27, s8
	s_cselect_b32 s8, s74, s12
	s_cselect_b32 s9, s75, s9
	s_cselect_b32 s13, s79, s15
	s_cselect_b32 s12, s78, s14
	v_lshl_add_u64 v[12:13], s[2:3], 0, v[176:177]
	s_add_i32 m0, s65, 0xc000
	ds_read_b128 v[150:153], v240
	ds_read_b128 v[154:157], v240 offset:1024
	ds_read_b128 v[182:185], v240 offset:2048
	ds_read_b128 v[186:189], v240 offset:3072
	ds_read_b128 v[190:193], v240 offset:4096
	ds_read_b128 v[194:197], v240 offset:5120
	ds_read_b128 v[198:201], v240 offset:6144
	ds_read_b128 v[202:205], v240 offset:7168
	global_load_lds_dwordx4 v[12:13], off
	v_lshl_add_u64 v[12:13], s[2:3], 0, v[178:179]
	s_add_i32 m0, s65, 0xe000
	s_nop 0
	global_load_lds_dwordx4 v[12:13], off
	s_waitcnt lgkmcnt(8)
	s_barrier
	s_waitcnt lgkmcnt(0)
	s_setprio 1
	v_mfma_f32_16x16x32_bf16 v[130:133], v[134:137], v[150:153], v[130:133]
	v_mfma_f32_16x16x32_bf16 v[126:129], v[142:145], v[150:153], v[126:129]
	v_mfma_f32_16x16x32_bf16 v[114:117], v[134:137], v[182:185], v[114:117]
	v_mfma_f32_16x16x32_bf16 v[110:113], v[142:145], v[182:185], v[110:113]
	v_mfma_f32_16x16x32_bf16 v[98:101], v[134:137], v[190:193], v[98:101]
	v_mfma_f32_16x16x32_bf16 v[94:97], v[142:145], v[190:193], v[94:97]
	v_mfma_f32_16x16x32_bf16 v[82:85], v[134:137], v[198:201], v[82:85]
	v_mfma_f32_16x16x32_bf16 v[78:81], v[142:145], v[198:201], v[78:81]
	v_mfma_f32_16x16x32_bf16 v[130:133], v[138:141], v[154:157], v[130:133]
	v_mfma_f32_16x16x32_bf16 v[126:129], v[146:149], v[154:157], v[126:129]
	v_mfma_f32_16x16x32_bf16 v[114:117], v[138:141], v[186:189], v[114:117]
	v_mfma_f32_16x16x32_bf16 v[110:113], v[146:149], v[186:189], v[110:113]
	v_mfma_f32_16x16x32_bf16 v[98:101], v[138:141], v[194:197], v[98:101]
	v_mfma_f32_16x16x32_bf16 v[94:97], v[146:149], v[194:197], v[94:97]
	v_mfma_f32_16x16x32_bf16 v[82:85], v[138:141], v[202:205], v[82:85]
	v_mfma_f32_16x16x32_bf16 v[78:81], v[146:149], v[202:205], v[78:81]
	s_setprio 0
	s_barrier
	s_add_i32 s36, 0, 0x14000
	s_add_i32 s31, s31, s64
	v_add_u32_e32 v10, s36, v234
	v_lshl_add_u64 v[210:211], s[12:13], 0, v[164:165]
	s_mov_b32 m0, s31
	ds_read_b128 v[206:209], v10
	ds_read_b128 v[242:245], v10 offset:1024
	ds_read_b128 v[246:249], v10 offset:2048
	ds_read_b128 v[250:253], v10 offset:3072
	global_load_lds_dwordx4 v[210:211], off
	v_lshl_add_u64 v[216:217], s[12:13], 0, v[160:161]
	s_add_i32 m0, s31, 0x2000
	s_nop 0
	global_load_lds_dwordx4 v[216:217], off
	s_barrier
	s_waitcnt lgkmcnt(0)
	s_setprio 1
	v_mfma_f32_16x16x32_bf16 v[122:125], v[206:209], v[150:153], v[122:125]
	v_mfma_f32_16x16x32_bf16 v[118:121], v[246:249], v[150:153], v[118:121]
	v_mfma_f32_16x16x32_bf16 v[106:109], v[206:209], v[182:185], v[106:109]
	v_mfma_f32_16x16x32_bf16 v[102:105], v[246:249], v[182:185], v[102:105]
	v_mfma_f32_16x16x32_bf16 v[90:93], v[206:209], v[190:193], v[90:93]
	v_mfma_f32_16x16x32_bf16 v[86:89], v[246:249], v[190:193], v[86:89]
	v_mfma_f32_16x16x32_bf16 v[74:77], v[206:209], v[198:201], v[74:77]
	v_mfma_f32_16x16x32_bf16 v[70:73], v[246:249], v[198:201], v[70:73]
	v_mfma_f32_16x16x32_bf16 v[122:125], v[242:245], v[154:157], v[122:125]
	v_mfma_f32_16x16x32_bf16 v[118:121], v[250:253], v[154:157], v[118:121]
	v_mfma_f32_16x16x32_bf16 v[106:109], v[242:245], v[186:189], v[106:109]
	v_mfma_f32_16x16x32_bf16 v[102:105], v[250:253], v[186:189], v[102:105]
	v_mfma_f32_16x16x32_bf16 v[90:93], v[242:245], v[194:197], v[90:93]
	v_mfma_f32_16x16x32_bf16 v[86:89], v[250:253], v[194:197], v[86:89]
	v_mfma_f32_16x16x32_bf16 v[74:77], v[242:245], v[202:205], v[74:77]
	v_mfma_f32_16x16x32_bf16 v[70:73], v[250:253], v[202:205], v[70:73]
	s_setprio 0
	s_mov_b32 m0, s65
	v_lshl_add_u64 v[222:223], s[8:9], 0, v[162:163]
	s_barrier
; #define PG8_STAGE(bufoff, gbase, voff) do { _Pragma("unroll") for (int _i = 0; _i < 2; ++_i) \
;         __builtin_amdgcn_global_load_lds((const unsigned*)((const char*)(gbase) + (voff)[_i]), (LAS unsigned*)(lds + (bufoff) + ldsw + _i * 8192), 16, 0, 0); } while (0)
; #define PG8_LDA(dst, b, h) do { _Pragma("unroll") for (int m = 0; m < 4; ++m) _Pragma("unroll") for (int k = 0; k < 2; ++k) dst[m][k] = *(const LAS bf16x8*)(lds + PG8_SA(b, h) + aoff + m * 2048 + k * 1024); } while (0)
; #define PG8_LDB(dst, b, h) do { _Pragma("unroll") for (int n = 0; n < 2; ++n) _Pragma("unroll") for (int k = 0; k < 2; ++k) dst[n][k] = *(const LAS bf16x8*)(lds + PG8_SB(b, h) + boff + n * 2048 + k * 1024); } while (0)
; #define PG8_MMA(ai, bj, At, Bt) do { __builtin_amdgcn_s_setprio(1); _Pragma("unroll") for (int m = 0; m < 4; ++m) _Pragma("unroll") for (int n = 0; n < 2; ++n) _Pragma("unroll") for (int k = 0; k < 2; ++k) \
;         acc[ai][bj][m][n] = __builtin_amdgcn_mfma_f32_16x16x32_bf16(Bt[n][k], At[m][k], acc[ai][bj][m][n], 0, 0, 0); __builtin_amdgcn_s_setprio(0); } while (0)
; #define PG8_WAIT_V(n) asm volatile("s_waitcnt vmcnt(" #n ")" ::: "memory")
; #define PG8_WAIT_L(n) asm volatile("s_waitcnt lgkmcnt(" #n ")" ::: "memory")
; #define PG8_BAR __builtin_amdgcn_s_barrier()
; #define PG8_SCHED __builtin_amdgcn_sched_barrier(0)
; __device__ __forceinline__ void gemm_phase(const int bid, const int nblk, LAS unsigned char* lds, const int garg, const int chunk, const Params& p) {
;     ...
;             PG8_LDA(At, 0, 1); PG8_STAGE(PG8_SA(0, 0), a2, voffA);
;             PG8_BAR; PG8_WAIT_L(0); PG8_MMA(1, 0, At, B0); PG8_BAR; PG8_SCHED;
;             PG8_STAGE(PG8_SB(0, 1), b2 + hstepB, voffB);
;             PG8_WAIT_V(6); PG8_BAR; PG8_MMA(1, 1, At, B1); PG8_BAR;
;             PG8_LDB(B0, 1, 0); PG8_SCHED; PG8_LDA(At, 1, 0); PG8_STAGE(PG8_SA(0, 1), a2 + hstepA, voffA);
;             PG8_WAIT_L(8); PG8_BAR; PG8_WAIT_L(0); PG8_MMA(0, 0, At, B0); PG8_BAR; PG8_SCHED;
;             PG8_LDB(B1, 1, 1); PG8_STAGE(PG8_SB(1, 0), b3, voffB);
;             PG8_BAR; PG8_WAIT_L(0); PG8_MMA(0, 1, At, B1); PG8_BAR;
	ds_read_b128 v[150:153], v240 offset:16384
	ds_read_b128 v[154:157], v240 offset:17408
	ds_read_b128 v[182:185], v240 offset:18432
	ds_read_b128 v[186:189], v240 offset:19456
	ds_read_b128 v[190:193], v240 offset:20480
	ds_read_b128 v[194:197], v240 offset:21504
	ds_read_b128 v[198:201], v240 offset:22528
	ds_read_b128 v[202:205], v240 offset:23552
	global_load_lds_dwordx4 v[222:223], off
	v_lshl_add_u64 v[224:225], s[8:9], 0, v[8:9]
	s_mov_b32 m0, s71
	s_nop 0
	global_load_lds_dwordx4 v[224:225], off
	s_barrier
	s_waitcnt lgkmcnt(0)
	s_setprio 1
	v_mfma_f32_16x16x32_bf16 v[66:69], v[134:137], v[150:153], v[66:69]
	v_mfma_f32_16x16x32_bf16 v[62:65], v[142:145], v[150:153], v[62:65]
	v_mfma_f32_16x16x32_bf16 v[50:53], v[134:137], v[182:185], v[50:53]
	v_mfma_f32_16x16x32_bf16 v[46:49], v[142:145], v[182:185], v[46:49]
	v_mfma_f32_16x16x32_bf16 v[34:37], v[134:137], v[190:193], v[34:37]
	v_mfma_f32_16x16x32_bf16 v[30:33], v[142:145], v[190:193], v[30:33]
	v_mfma_f32_16x16x32_bf16 v[18:21], v[134:137], v[198:201], v[18:21]
	v_mfma_f32_16x16x32_bf16 v[12:15], v[142:145], v[198:201], v[14:17]
	v_mfma_f32_16x16x32_bf16 v[66:69], v[138:141], v[154:157], v[66:69]
	v_mfma_f32_16x16x32_bf16 v[62:65], v[146:149], v[154:157], v[62:65]
	v_mfma_f32_16x16x32_bf16 v[50:53], v[138:141], v[186:189], v[50:53]
	v_mfma_f32_16x16x32_bf16 v[46:49], v[146:149], v[186:189], v[46:49]
	v_mfma_f32_16x16x32_bf16 v[34:37], v[138:141], v[194:197], v[34:37]
	v_mfma_f32_16x16x32_bf16 v[30:33], v[146:149], v[194:197], v[30:33]
	v_mfma_f32_16x16x32_bf16 v[18:21], v[138:141], v[202:205], v[18:21]
	v_mfma_f32_16x16x32_bf16 v[12:15], v[146:149], v[202:205], v[12:15]
	s_setprio 0
	s_barrier
	s_add_u32 s12, s12, s66
	s_addc_u32 s13, s13, s67
	s_add_i32 s31, s36, s64
	v_lshl_add_u64 v[220:221], s[12:13], 0, v[164:165]
	s_mov_b32 m0, s31
	v_lshl_add_u64 v[226:227], s[12:13], 0, v[160:161]
	global_load_lds_dwordx4 v[220:221], off
	s_add_i32 m0, s31, 0x2000
	s_nop 0
	global_load_lds_dwordx4 v[226:227], off
	s_waitcnt vmcnt(6)
	s_barrier
	s_setprio 1
	v_mfma_f32_16x16x32_bf16 v[58:61], v[206:209], v[150:153], v[58:61]
	v_mfma_f32_16x16x32_bf16 v[54:57], v[246:249], v[150:153], v[54:57]
	v_mfma_f32_16x16x32_bf16 v[42:45], v[206:209], v[182:185], v[42:45]
	v_mfma_f32_16x16x32_bf16 v[38:41], v[246:249], v[182:185], v[38:41]
	v_mfma_f32_16x16x32_bf16 v[26:29], v[206:209], v[190:193], v[26:29]
	v_mfma_f32_16x16x32_bf16 v[22:25], v[246:249], v[190:193], v[22:25]
	v_mfma_f32_16x16x32_bf16 v[4:7], v[206:209], v[198:201], v[4:7]
	v_mfma_f32_16x16x32_bf16 v[0:3], v[246:249], v[198:201], v[0:3]
	v_mfma_f32_16x16x32_bf16 v[58:61], v[242:245], v[154:157], v[58:61]
	v_mfma_f32_16x16x32_bf16 v[54:57], v[250:253], v[154:157], v[54:57]
	v_mfma_f32_16x16x32_bf16 v[42:45], v[242:245], v[186:189], v[42:45]
	v_mfma_f32_16x16x32_bf16 v[38:41], v[250:253], v[186:189], v[38:41]
	v_mfma_f32_16x16x32_bf16 v[26:29], v[242:245], v[194:197], v[26:29]
	v_mfma_f32_16x16x32_bf16 v[22:25], v[250:253], v[194:197], v[22:25]
	v_mfma_f32_16x16x32_bf16 v[4:7], v[242:245], v[202:205], v[4:7]
	v_mfma_f32_16x16x32_bf16 v[0:3], v[250:253], v[202:205], v[0:3]
	s_setprio 0
.Lk_mid:
	s_add_i32 s12, 0, 0x18000
	v_add_u32_e32 v10, s12, v234
	s_barrier
	ds_read_b128 v[134:137], v10
	ds_read_b128 v[138:141], v10 offset:1024
	ds_read_b128 v[142:145], v10 offset:2048
	ds_read_b128 v[146:149], v10 offset:3072
	s_add_u32 s8, s8, s88
	s_addc_u32 s9, s9, s89
	s_mov_b32 m0, s63
	v_lshl_add_u64 v[16:17], s[8:9], 0, v[162:163]
	ds_read_b128 v[150:153], v240 offset:32768
	ds_read_b128 v[154:157], v240 offset:33792
	ds_read_b128 v[182:185], v240 offset:34816
	ds_read_b128 v[186:189], v240 offset:35840
	ds_read_b128 v[190:193], v240 offset:36864
	ds_read_b128 v[194:197], v240 offset:37888
	ds_read_b128 v[198:201], v240 offset:38912
	ds_read_b128 v[202:205], v240 offset:39936
	global_load_lds_dwordx4 v[16:17], off
	v_lshl_add_u64 v[16:17], s[8:9], 0, v[8:9]
	s_mov_b32 m0, s19
	s_nop 0
	global_load_lds_dwordx4 v[16:17], off
	s_waitcnt lgkmcnt(8)
	s_barrier
	s_waitcnt lgkmcnt(0)
	s_setprio 1
	v_mfma_f32_16x16x32_bf16 v[130:133], v[134:137], v[150:153], v[130:133]
	v_mfma_f32_16x16x32_bf16 v[126:129], v[142:145], v[150:153], v[126:129]
	v_mfma_f32_16x16x32_bf16 v[114:117], v[134:137], v[182:185], v[114:117]
	v_mfma_f32_16x16x32_bf16 v[110:113], v[142:145], v[182:185], v[110:113]
	v_mfma_f32_16x16x32_bf16 v[98:101], v[134:137], v[190:193], v[98:101]
	v_mfma_f32_16x16x32_bf16 v[94:97], v[142:145], v[190:193], v[94:97]
	v_mfma_f32_16x16x32_bf16 v[82:85], v[134:137], v[198:201], v[82:85]
	v_mfma_f32_16x16x32_bf16 v[78:81], v[142:145], v[198:201], v[78:81]
	v_mfma_f32_16x16x32_bf16 v[130:133], v[138:141], v[154:157], v[130:133]
	v_mfma_f32_16x16x32_bf16 v[126:129], v[146:149], v[154:157], v[126:129]
	v_mfma_f32_16x16x32_bf16 v[114:117], v[138:141], v[186:189], v[114:117]
	v_mfma_f32_16x16x32_bf16 v[110:113], v[146:149], v[186:189], v[110:113]
	v_mfma_f32_16x16x32_bf16 v[98:101], v[138:141], v[194:197], v[98:101]
	v_mfma_f32_16x16x32_bf16 v[94:97], v[146:149], v[194:197], v[94:97]
	v_mfma_f32_16x16x32_bf16 v[82:85], v[138:141], v[202:205], v[82:85]
	v_mfma_f32_16x16x32_bf16 v[78:81], v[146:149], v[202:205], v[78:81]
	s_setprio 0
	s_barrier
; #define PG8_STAGE(bufoff, gbase, voff) do { _Pragma("unroll") for (int _i = 0; _i < 2; ++_i) \
;         __builtin_amdgcn_global_load_lds((const unsigned*)((const char*)(gbase) + (voff)[_i]), (LAS unsigned*)(lds + (bufoff) + ldsw + _i * 8192), 16, 0, 0); } while (0)
; #define PG8_LDA(dst, b, h) do { _Pragma("unroll") for (int m = 0; m < 4; ++m) _Pragma("unroll") for (int k = 0; k < 2; ++k) dst[m][k] = *(const LAS bf16x8*)(lds + PG8_SA(b, h) + aoff + m * 2048 + k * 1024); } while (0)
; #define PG8_LDB(dst, b, h) do { _Pragma("unroll") for (int n = 0; n < 2; ++n) _Pragma("unroll") for (int k = 0; k < 2; ++k) dst[n][k] = *(const LAS bf16x8*)(lds + PG8_SB(b, h) + boff + n * 2048 + k * 1024); } while (0)
; #define PG8_MMA(ai, bj, At, Bt) do { __builtin_amdgcn_s_setprio(1); _Pragma("unroll") for (int m = 0; m < 4; ++m) _Pragma("unroll") for (int n = 0; n < 2; ++n) _Pragma("unroll") for (int k = 0; k < 2; ++k) \
;         acc[ai][bj][m][n] = __builtin_amdgcn_mfma_f32_16x16x32_bf16(Bt[n][k], At[m][k], acc[ai][bj][m][n], 0, 0, 0); __builtin_amdgcn_s_setprio(0); } while (0)
; #define PG8_WAIT_V(n) asm volatile("s_waitcnt vmcnt(" #n ")" ::: "memory")
; #define PG8_WAIT_L(n) asm volatile("s_waitcnt lgkmcnt(" #n ")" ::: "memory")
; #define PG8_BAR __builtin_amdgcn_s_barrier()
; #define PG8_SCHED __builtin_amdgcn_sched_barrier(0)
; __device__ __forceinline__ void gemm_phase(const int bid, const int nblk, LAS unsigned char* lds, const int garg, const int chunk, const Params& p) {
;     ...
;             PG8_WAIT_L(8); PG8_BAR; PG8_WAIT_L(0); PG8_MMA(0, 0, At, B0); PG8_BAR; PG8_SCHED;
;             PG8_LDB(B1, 1, 1); PG8_STAGE(PG8_SB(1, 0), b3, voffB);
;             PG8_BAR; PG8_WAIT_L(0); PG8_MMA(0, 1, At, B1); PG8_BAR;
;             PG8_LDA(At, 1, 1); PG8_STAGE(PG8_SA(1, 0), a3, voffA);
;             PG8_BAR; PG8_WAIT_L(0); PG8_MMA(1, 0, At, B0); PG8_BAR; PG8_SCHED;
;             PG8_STAGE(PG8_SB(1, 1), b3 + hstepB, voffB);
;             PG8_WAIT_V(6); PG8_BAR; PG8_MMA(1, 1, At, B1); PG8_BAR;
	s_add_i32 s8, 0, 0x1c000
	s_add_i32 s9, s12, s64
	v_add_u32_e32 v10, s8, v234
	v_lshl_add_u64 v[16:17], v[210:211], 0, s[92:93]
	s_mov_b32 m0, s9
	ds_read_b128 v[206:209], v10
	ds_read_b128 v[242:245], v10 offset:1024
	ds_read_b128 v[246:249], v10 offset:2048
	ds_read_b128 v[250:253], v10 offset:3072
	global_load_lds_dwordx4 v[16:17], off
	v_lshl_add_u64 v[16:17], v[216:217], 0, s[92:93]
	s_add_i32 m0, s9, 0x2000
	s_nop 0
	global_load_lds_dwordx4 v[16:17], off
	s_barrier
	s_waitcnt lgkmcnt(0)
	s_setprio 1
	v_mfma_f32_16x16x32_bf16 v[122:125], v[206:209], v[150:153], v[122:125]
	v_mfma_f32_16x16x32_bf16 v[118:121], v[246:249], v[150:153], v[118:121]
	v_mfma_f32_16x16x32_bf16 v[106:109], v[206:209], v[182:185], v[106:109]
	v_mfma_f32_16x16x32_bf16 v[102:105], v[246:249], v[182:185], v[102:105]
	v_mfma_f32_16x16x32_bf16 v[90:93], v[206:209], v[190:193], v[90:93]
	v_mfma_f32_16x16x32_bf16 v[86:89], v[246:249], v[190:193], v[86:89]
	v_mfma_f32_16x16x32_bf16 v[74:77], v[206:209], v[198:201], v[74:77]
	v_mfma_f32_16x16x32_bf16 v[70:73], v[246:249], v[198:201], v[70:73]
	v_mfma_f32_16x16x32_bf16 v[122:125], v[242:245], v[154:157], v[122:125]
	v_mfma_f32_16x16x32_bf16 v[118:121], v[250:253], v[154:157], v[118:121]
	v_mfma_f32_16x16x32_bf16 v[106:109], v[242:245], v[186:189], v[106:109]
	v_mfma_f32_16x16x32_bf16 v[102:105], v[250:253], v[186:189], v[102:105]
	v_mfma_f32_16x16x32_bf16 v[90:93], v[242:245], v[194:197], v[90:93]
	v_mfma_f32_16x16x32_bf16 v[86:89], v[250:253], v[194:197], v[86:89]
	v_mfma_f32_16x16x32_bf16 v[74:77], v[242:245], v[202:205], v[74:77]
	v_mfma_f32_16x16x32_bf16 v[70:73], v[250:253], v[202:205], v[70:73]
	s_setprio 0
	s_mov_b32 m0, s70
	v_lshl_add_u64 v[16:17], v[222:223], 0, s[92:93]
	s_barrier
	ds_read_b128 v[150:153], v240 offset:49152
	ds_read_b128 v[154:157], v240 offset:50176
	ds_read_b128 v[182:185], v240 offset:51200
	ds_read_b128 v[186:189], v240 offset:52224
	ds_read_b128 v[190:193], v240 offset:53248
	ds_read_b128 v[194:197], v240 offset:54272
	ds_read_b128 v[198:201], v240 offset:55296
	ds_read_b128 v[202:205], v240 offset:56320
	global_load_lds_dwordx4 v[16:17], off
	v_lshl_add_u64 v[16:17], v[224:225], 0, s[92:93]
	s_mov_b32 m0, s54
	s_nop 0
	global_load_lds_dwordx4 v[16:17], off
	s_barrier
	s_waitcnt lgkmcnt(0)
	s_setprio 1
	v_mfma_f32_16x16x32_bf16 v[66:69], v[134:137], v[150:153], v[66:69]
	v_mfma_f32_16x16x32_bf16 v[62:65], v[142:145], v[150:153], v[62:65]
	v_mfma_f32_16x16x32_bf16 v[50:53], v[134:137], v[182:185], v[50:53]
	v_mfma_f32_16x16x32_bf16 v[46:49], v[142:145], v[182:185], v[46:49]
	v_mfma_f32_16x16x32_bf16 v[34:37], v[134:137], v[190:193], v[34:37]
	v_mfma_f32_16x16x32_bf16 v[30:33], v[142:145], v[190:193], v[30:33]
	v_mfma_f32_16x16x32_bf16 v[16:19], v[134:137], v[198:201], v[18:21]
	v_mfma_f32_16x16x32_bf16 v[12:15], v[142:145], v[198:201], v[12:15]
	v_mfma_f32_16x16x32_bf16 v[66:69], v[138:141], v[154:157], v[66:69]
	v_mfma_f32_16x16x32_bf16 v[62:65], v[146:149], v[154:157], v[62:65]
	v_mfma_f32_16x16x32_bf16 v[50:53], v[138:141], v[186:189], v[50:53]
	v_mfma_f32_16x16x32_bf16 v[46:49], v[146:149], v[186:189], v[46:49]
	v_mfma_f32_16x16x32_bf16 v[34:37], v[138:141], v[194:197], v[34:37]
	v_mfma_f32_16x16x32_bf16 v[30:33], v[146:149], v[194:197], v[30:33]
	v_mfma_f32_16x16x32_bf16 v[18:21], v[138:141], v[202:205], v[16:19]
	v_mfma_f32_16x16x32_bf16 v[14:17], v[146:149], v[202:205], v[12:15]
	s_setprio 0
	s_barrier
	s_add_i32 s8, s8, s64
	v_lshl_add_u64 v[12:13], v[220:221], 0, s[92:93]
	s_mov_b32 m0, s8
	s_nop 0
	global_load_lds_dwordx4 v[12:13], off
	v_lshl_add_u64 v[12:13], v[226:227], 0, s[92:93]
	s_add_i32 m0, s8, 0x2000
	s_nop 0
	global_load_lds_dwordx4 v[12:13], off
	s_waitcnt vmcnt(6)
	s_barrier
	s_setprio 1
	v_mfma_f32_16x16x32_bf16 v[58:61], v[206:209], v[150:153], v[58:61]
	v_mfma_f32_16x16x32_bf16 v[54:57], v[246:249], v[150:153], v[54:57]
	v_mfma_f32_16x16x32_bf16 v[42:45], v[206:209], v[182:185], v[42:45]
	v_mfma_f32_16x16x32_bf16 v[38:41], v[246:249], v[182:185], v[38:41]
	v_mfma_f32_16x16x32_bf16 v[26:29], v[206:209], v[190:193], v[26:29]
	v_mfma_f32_16x16x32_bf16 v[22:25], v[246:249], v[190:193], v[22:25]
	v_mfma_f32_16x16x32_bf16 v[4:7], v[206:209], v[198:201], v[4:7]
	v_mfma_f32_16x16x32_bf16 v[0:3], v[246:249], v[198:201], v[0:3]
	v_mfma_f32_16x16x32_bf16 v[58:61], v[242:245], v[154:157], v[58:61]
	v_mfma_f32_16x16x32_bf16 v[54:57], v[250:253], v[154:157], v[54:57]
	v_mfma_f32_16x16x32_bf16 v[42:45], v[242:245], v[186:189], v[42:45]
	v_mfma_f32_16x16x32_bf16 v[38:41], v[250:253], v[186:189], v[38:41]
	v_mfma_f32_16x16x32_bf16 v[26:29], v[242:245], v[194:197], v[26:29]
	v_mfma_f32_16x16x32_bf16 v[22:25], v[250:253], v[194:197], v[22:25]
	v_mfma_f32_16x16x32_bf16 v[4:7], v[242:245], v[202:205], v[4:7]
	v_mfma_f32_16x16x32_bf16 v[0:3], v[250:253], v[202:205], v[0:3]
	s_setprio 0
	s_add_u32 s2, s2, 0x100
	s_addc_u32 s3, s3, 0
	s_add_u32 s14, s14, 0x100
	s_addc_u32 s15, s15, 0
	s_cmp_ge_i32 s30, s55
	s_mov_b32 s8, s30
	s_barrier
	s_cbranch_scc0 .LBB0_441
	s_branch .LBB0_443
